# s5_state_block: issue all 32 U-fragment loads upfront, counted waits, LDS reads 4 steps ahead
# baseline (speedup 1.0000x reference)
; #define LAS __attribute__((address_space(3)))
; #define LBAR() do { asm volatile("s_waitcnt lgkmcnt(0)" ::: "memory"); __builtin_amdgcn_s_barrier(); asm volatile("" ::: "memory"); } while (0)
; __device__ __forceinline__ void s5_state_block(LAS unsigned char* lds, const bf16* __restrict__ WST, const bf16* __restrict__ U, float* SC, int vb, int tid, int wave, int lane) {
;     ...
;     LBAR();
;     { const u32x4* src = (const u32x4*)(WST + (size_t)g * 128 * 512);
;       u32x4 tmp[16];
; #pragma unroll
;       for (int i = 0; i < 16; ++i) tmp[i] = src[tid + 512 * i];
; #pragma unroll
;       for (int i = 0; i < 16; ++i) { const int chunk = tid + 512 * i, row = chunk >> 6, ch = chunk & 63; *(LAS u32x4*)(lds + row * WROW + ch * 16) = tmp[i]; } }
;     LBAR();
;     const int half = wave & 1, ct = 4 * (vb & 3) + (wave >> 1), r = lane & 31, h = lane >> 5, c = ct * 32 + r;
;     f32x16 acc[2];
; #pragma unroll
;     for (int i = 0; i < 2; ++i)
; #pragma unroll
;         for (int e = 0; e < 16; ++e) acc[i][e] = 0.f;
;     const bf16* ub = U + ((size_t)g * S + (size_t)c * 32) * 16 + 8 * h;
;     const LAS unsigned char* wl = lds + (64 * half + r) * WROW + h * 16;
;     bf16x8 bfr[32];
; #pragma unroll
;     for (int ks = 0; ks < 32; ++ks) bfr[ks] = *(const bf16x8*)(ub + ks * 16);
.LBB0_598:
	s_ashr_i32 s4, s17, 2
	s_ashr_i32 s5, s4, 31
	s_lshl_b64 s[6:7], s[4:5], 17
	s_add_u32 s6, s30, s6
	s_addc_u32 s7, s31, s7
	s_waitcnt vmcnt(24)
	v_lshl_add_u64 v[94:95], s[6:7], 0, v[34:35]
	v_add_co_u32_e32 v4, vcc, s9, v94
	s_and_b32 s26, s3, 12
	s_nop 0
	v_addc_co_u32_e32 v5, vcc, 0, v95, vcc
	v_add_co_u32_e32 v12, vcc, s10, v94
	s_lshl_b64 s[24:25], s[4:5], 19
	s_nop 0
	v_addc_co_u32_e32 v13, vcc, 0, v95, vcc
	v_add_co_u32_e32 v20, vcc, s11, v94
	s_add_i32 s26, s26, s2
	s_nop 0
	v_addc_co_u32_e32 v21, vcc, 0, v95, vcc
	v_add_co_u32_e32 v28, vcc, s12, v94
	v_lshl_or_b32 v32, s26, 5, v185
	s_nop 0
	v_addc_co_u32_e32 v29, vcc, 0, v95, vcc
	v_add_co_u32_e32 v70, vcc, s13, v94
	s_add_u32 s24, s86, s24
	s_nop 0
	v_addc_co_u32_e32 v71, vcc, 0, v95, vcc
	v_add_co_u32_e32 v78, vcc, s14, v94
	s_addc_u32 s25, s87, s25
	s_nop 0
	v_addc_co_u32_e32 v79, vcc, 0, v95, vcc
	v_lshlrev_b64 v[14:15], 10, v[32:33]
	v_add_co_u32_e32 v86, vcc, s15, v94
	s_waitcnt lgkmcnt(0)
	s_barrier
	v_lshl_add_u64 v[22:23], s[24:25], 0, v[14:15]
	v_addc_co_u32_e32 v87, vcc, 0, v95, vcc
	global_load_dwordx4 v[0:3], v34, s[6:7]
	s_nop 0
	global_load_dwordx4 v[4:7], v[4:5], off
	s_nop 0
	global_load_dwordx4 v[8:11], v43, s[6:7]
	s_nop 0
	global_load_dwordx4 v[12:15], v[12:13], off
	s_nop 0
	global_load_dwordx4 v[16:19], v44, s[6:7]
	v_lshl_add_u64 v[40:41], v[22:23], 0, v[36:37]
	global_load_dwordx4 v[20:23], v[20:21], off
	s_nop 0
	global_load_dwordx4 v[24:27], v45, s[6:7]
	s_nop 0
	global_load_dwordx4 v[28:31], v[28:29], off
	s_nop 0
	global_load_dwordx4 v[66:69], v46, s[6:7]
	s_nop 0
	global_load_dwordx4 v[70:73], v[70:71], off
	s_nop 0
	global_load_dwordx4 v[74:77], v47, s[6:7]
	s_nop 0
	global_load_dwordx4 v[78:81], v[78:79], off
	s_nop 0
	global_load_dwordx4 v[82:85], v48, s[6:7]
	s_nop 0
	global_load_dwordx4 v[86:89], v[86:87], off
	s_nop 0
	global_load_dwordx4 v[90:93], v49, s[6:7]
	v_add_co_u32_e32 v94, vcc, s16, v94
	s_lshl_b64 s[4:5], s[4:5], 18
	s_nop 0
	v_addc_co_u32_e32 v95, vcc, 0, v95, vcc
	global_load_dwordx4 v[94:97], v[94:95], off
	global_load_dwordx4 v[100:103], v[40:41], off
	global_load_dwordx4 v[104:107], v[40:41], off offset:32
	global_load_dwordx4 v[108:111], v[40:41], off offset:64
	global_load_dwordx4 v[112:115], v[40:41], off offset:96
	global_load_dwordx4 v[116:119], v[40:41], off offset:128
	global_load_dwordx4 v[120:123], v[40:41], off offset:160
	global_load_dwordx4 v[124:127], v[40:41], off offset:192
	global_load_dwordx4 v[128:131], v[40:41], off offset:224
	global_load_dwordx4 v[132:135], v[40:41], off offset:256
	global_load_dwordx4 v[136:139], v[40:41], off offset:288
	global_load_dwordx4 v[140:143], v[40:41], off offset:320
	global_load_dwordx4 v[144:147], v[40:41], off offset:352
	global_load_dwordx4 v[148:151], v[40:41], off offset:384
	global_load_dwordx4 v[152:155], v[40:41], off offset:416
	global_load_dwordx4 v[156:159], v[40:41], off offset:448
	global_load_dwordx4 v[160:163], v[40:41], off offset:480
	global_load_dwordx4 v[164:167], v[40:41], off offset:512
	global_load_dwordx4 v[168:171], v[40:41], off offset:544
	global_load_dwordx4 v[172:175], v[40:41], off offset:576
	global_load_dwordx4 v[176:179], v[40:41], off offset:608
	global_load_dwordx4 v[180:183], v[40:41], off offset:640
	global_load_dwordx4 v[188:191], v[40:41], off offset:672
	global_load_dwordx4 v[192:195], v[40:41], off offset:704
	global_load_dwordx4 v[196:199], v[40:41], off offset:736
	global_load_dwordx4 v[200:203], v[40:41], off offset:768
	global_load_dwordx4 v[204:207], v[40:41], off offset:800
	global_load_dwordx4 v[208:211], v[40:41], off offset:832
	global_load_dwordx4 v[212:215], v[40:41], off offset:864
	global_load_dwordx4 v[216:219], v[40:41], off offset:896
	global_load_dwordx4 v[220:223], v[40:41], off offset:928
	global_load_dwordx4 v[224:227], v[40:41], off offset:960
	global_load_dwordx4 v[228:231], v[40:41], off offset:992
	s_add_u32 s4, s34, s4
	s_addc_u32 s5, s35, s5
	s_add_i32 s17, s17, s28
	s_add_i32 s3, s3, s8
	s_cmpk_lt_i32 s17, 0x100
	s_waitcnt vmcnt(47)
	ds_write_b128 v50, v[0:3]
	s_waitcnt vmcnt(46)
	ds_write_b128 v51, v[4:7]
	s_waitcnt vmcnt(45)
	ds_write_b128 v52, v[8:11]
	s_waitcnt vmcnt(44)
	ds_write_b128 v53, v[12:15]
	s_waitcnt vmcnt(43)
	ds_write_b128 v54, v[16:19]
	s_waitcnt vmcnt(42)
	ds_write_b128 v55, v[20:23]
	s_waitcnt vmcnt(41)
	ds_write_b128 v56, v[24:27]
	s_waitcnt vmcnt(40)
	ds_write_b128 v57, v[28:31]
	s_waitcnt vmcnt(39)
	ds_write_b128 v58, v[66:69]
	s_waitcnt vmcnt(38)
	ds_write_b128 v59, v[70:73]
	s_waitcnt vmcnt(37)
	ds_write_b128 v60, v[74:77]
	s_waitcnt vmcnt(36)
	ds_write_b128 v61, v[78:81]
	s_waitcnt vmcnt(35)
	ds_write_b128 v62, v[82:85]
	s_waitcnt vmcnt(34)
	ds_write_b128 v63, v[86:89]
	s_waitcnt vmcnt(33)
	ds_write_b128 v64, v[90:93]
	s_waitcnt vmcnt(32)
	ds_write_b128 v65, v[94:97]
	s_waitcnt lgkmcnt(0)
	s_barrier
; #define LAS __attribute__((address_space(3)))
; __device__ __forceinline__ void s5_state_block(LAS unsigned char* lds, const bf16* __restrict__ WST, const bf16* __restrict__ U, float* SC, int vb, int tid, int wave, int lane) {
;     ...
;     const bf16* ub = U + ((size_t)g * S + (size_t)c * 32) * 16 + 8 * h;
;     const LAS unsigned char* wl = lds + (64 * half + r) * WROW + h * 16;
;     bf16x8 bfr[32];
; #pragma unroll
;     for (int ks = 0; ks < 32; ++ks) bfr[ks] = *(const bf16x8*)(ub + ks * 16);
; #pragma unroll
;     for (int ks = 0; ks < 32; ++ks) {
; #pragma unroll
;         for (int rt = 0; rt < 2; ++rt) { const bf16x8 av = *(const LAS bf16x8*)(wl + rt * 32 * WROW + ks * 32); acc[rt] = __builtin_amdgcn_mfma_f32_32x32x16_bf16(av, bfr[ks], acc[rt], 0, 0, 0); }
;     }
	ds_read_b128 v[66:69], v42
	ds_read_b128 v[70:73], v42 offset:33280
	ds_read_b128 v[74:77], v42 offset:32
	ds_read_b128 v[78:81], v42 offset:33312
	ds_read_b128 v[82:85], v42 offset:64
	ds_read_b128 v[86:89], v42 offset:33344
	ds_read_b128 v[90:93], v42 offset:96
	ds_read_b128 v[94:97], v42 offset:33376
	s_waitcnt vmcnt(31) lgkmcnt(7)
	v_mfma_f32_32x32x16_bf16 v[0:15], v[66:69], v[100:103], 0
	s_waitcnt lgkmcnt(6)
	v_mfma_f32_32x32x16_bf16 v[16:31], v[70:73], v[100:103], 0
	ds_read_b128 v[66:69], v42 offset:128
	ds_read_b128 v[70:73], v42 offset:33408
	s_waitcnt vmcnt(30) lgkmcnt(7)
	v_mfma_f32_32x32x16_bf16 v[0:15], v[74:77], v[104:107], v[0:15]
	s_waitcnt lgkmcnt(6)
	v_mfma_f32_32x32x16_bf16 v[16:31], v[78:81], v[104:107], v[16:31]
	ds_read_b128 v[74:77], v42 offset:160
	ds_read_b128 v[78:81], v42 offset:33440
	s_waitcnt vmcnt(29) lgkmcnt(7)
	v_mfma_f32_32x32x16_bf16 v[0:15], v[82:85], v[108:111], v[0:15]
	s_waitcnt lgkmcnt(6)
	v_mfma_f32_32x32x16_bf16 v[16:31], v[86:89], v[108:111], v[16:31]
	ds_read_b128 v[82:85], v42 offset:192
	ds_read_b128 v[86:89], v42 offset:33472
	s_waitcnt vmcnt(28) lgkmcnt(7)
	v_mfma_f32_32x32x16_bf16 v[0:15], v[90:93], v[112:115], v[0:15]
	s_waitcnt lgkmcnt(6)
	v_mfma_f32_32x32x16_bf16 v[16:31], v[94:97], v[112:115], v[16:31]
	ds_read_b128 v[90:93], v42 offset:224
	ds_read_b128 v[94:97], v42 offset:33504
	s_waitcnt vmcnt(27) lgkmcnt(7)
	v_mfma_f32_32x32x16_bf16 v[0:15], v[66:69], v[116:119], v[0:15]
	s_waitcnt lgkmcnt(6)
	v_mfma_f32_32x32x16_bf16 v[16:31], v[70:73], v[116:119], v[16:31]
	ds_read_b128 v[66:69], v42 offset:256
	ds_read_b128 v[70:73], v42 offset:33536
	s_waitcnt vmcnt(26) lgkmcnt(7)
	v_mfma_f32_32x32x16_bf16 v[0:15], v[74:77], v[120:123], v[0:15]
	s_waitcnt lgkmcnt(6)
	v_mfma_f32_32x32x16_bf16 v[16:31], v[78:81], v[120:123], v[16:31]
	ds_read_b128 v[74:77], v42 offset:288
	ds_read_b128 v[78:81], v42 offset:33568
	s_waitcnt vmcnt(25) lgkmcnt(7)
	v_mfma_f32_32x32x16_bf16 v[0:15], v[82:85], v[124:127], v[0:15]
	s_waitcnt lgkmcnt(6)
	v_mfma_f32_32x32x16_bf16 v[16:31], v[86:89], v[124:127], v[16:31]
	ds_read_b128 v[82:85], v42 offset:320
	ds_read_b128 v[86:89], v42 offset:33600
	s_waitcnt vmcnt(24) lgkmcnt(7)
	v_mfma_f32_32x32x16_bf16 v[0:15], v[90:93], v[128:131], v[0:15]
	s_waitcnt lgkmcnt(6)
	v_mfma_f32_32x32x16_bf16 v[16:31], v[94:97], v[128:131], v[16:31]
	ds_read_b128 v[90:93], v42 offset:352
	ds_read_b128 v[94:97], v42 offset:33632
	s_waitcnt vmcnt(23) lgkmcnt(7)
	v_mfma_f32_32x32x16_bf16 v[0:15], v[66:69], v[132:135], v[0:15]
	s_waitcnt lgkmcnt(6)
	v_mfma_f32_32x32x16_bf16 v[16:31], v[70:73], v[132:135], v[16:31]
	ds_read_b128 v[66:69], v42 offset:384
	ds_read_b128 v[70:73], v42 offset:33664
	s_waitcnt vmcnt(22) lgkmcnt(7)
	v_mfma_f32_32x32x16_bf16 v[0:15], v[74:77], v[136:139], v[0:15]
	s_waitcnt lgkmcnt(6)
	v_mfma_f32_32x32x16_bf16 v[16:31], v[78:81], v[136:139], v[16:31]
	ds_read_b128 v[74:77], v42 offset:416
	ds_read_b128 v[78:81], v42 offset:33696
	s_waitcnt vmcnt(21) lgkmcnt(7)
	v_mfma_f32_32x32x16_bf16 v[0:15], v[82:85], v[140:143], v[0:15]
	s_waitcnt lgkmcnt(6)
	v_mfma_f32_32x32x16_bf16 v[16:31], v[86:89], v[140:143], v[16:31]
	ds_read_b128 v[82:85], v42 offset:448
	ds_read_b128 v[86:89], v42 offset:33728
	s_waitcnt vmcnt(20) lgkmcnt(7)
	v_mfma_f32_32x32x16_bf16 v[0:15], v[90:93], v[144:147], v[0:15]
	s_waitcnt lgkmcnt(6)
	v_mfma_f32_32x32x16_bf16 v[16:31], v[94:97], v[144:147], v[16:31]
	ds_read_b128 v[90:93], v42 offset:480
	ds_read_b128 v[94:97], v42 offset:33760
	s_waitcnt vmcnt(19) lgkmcnt(7)
	v_mfma_f32_32x32x16_bf16 v[0:15], v[66:69], v[148:151], v[0:15]
	s_waitcnt lgkmcnt(6)
	v_mfma_f32_32x32x16_bf16 v[16:31], v[70:73], v[148:151], v[16:31]
	ds_read_b128 v[66:69], v42 offset:512
	ds_read_b128 v[70:73], v42 offset:33792
	s_waitcnt vmcnt(18) lgkmcnt(7)
	v_mfma_f32_32x32x16_bf16 v[0:15], v[74:77], v[152:155], v[0:15]
	s_waitcnt lgkmcnt(6)
	v_mfma_f32_32x32x16_bf16 v[16:31], v[78:81], v[152:155], v[16:31]
	ds_read_b128 v[74:77], v42 offset:544
	ds_read_b128 v[78:81], v42 offset:33824
	s_waitcnt vmcnt(17) lgkmcnt(7)
	v_mfma_f32_32x32x16_bf16 v[0:15], v[82:85], v[156:159], v[0:15]
	s_waitcnt lgkmcnt(6)
	v_mfma_f32_32x32x16_bf16 v[16:31], v[86:89], v[156:159], v[16:31]
	ds_read_b128 v[82:85], v42 offset:576
	ds_read_b128 v[86:89], v42 offset:33856
	s_waitcnt vmcnt(16) lgkmcnt(7)
	v_mfma_f32_32x32x16_bf16 v[0:15], v[90:93], v[160:163], v[0:15]
	s_waitcnt lgkmcnt(6)
	v_mfma_f32_32x32x16_bf16 v[16:31], v[94:97], v[160:163], v[16:31]
	ds_read_b128 v[90:93], v42 offset:608
	ds_read_b128 v[94:97], v42 offset:33888
	s_waitcnt vmcnt(15) lgkmcnt(7)
; #define LAS __attribute__((address_space(3)))
; __device__ __forceinline__ void s5_state_block(LAS unsigned char* lds, const bf16* __restrict__ WST, const bf16* __restrict__ U, float* SC, int vb, int tid, int wave, int lane) {
;     ...
;     for (int ks = 0; ks < 32; ++ks) {
; #pragma unroll
;         for (int rt = 0; rt < 2; ++rt) { const bf16x8 av = *(const LAS bf16x8*)(wl + rt * 32 * WROW + ks * 32); acc[rt] = __builtin_amdgcn_mfma_f32_32x32x16_bf16(av, bfr[ks], acc[rt], 0, 0, 0); }
;     }
;     float* o = SC + ((size_t)g * SNC + c) * 128 + 64 * half;
; #pragma unroll
;     for (int rt = 0; rt < 2; ++rt)
; #pragma unroll
;         for (int eg = 0; eg < 4; ++eg) { f32x4 v = {acc[rt][4 * eg], acc[rt][4 * eg + 1], acc[rt][4 * eg + 2], acc[rt][4 * eg + 3]}; *(f32x4*)(o + 32 * rt + 8 * eg + 4 * h) = v; }
	v_mfma_f32_32x32x16_bf16 v[0:15], v[66:69], v[164:167], v[0:15]
	s_waitcnt lgkmcnt(6)
	v_mfma_f32_32x32x16_bf16 v[16:31], v[70:73], v[164:167], v[16:31]
	ds_read_b128 v[66:69], v42 offset:640
	ds_read_b128 v[70:73], v42 offset:33920
	s_waitcnt vmcnt(14) lgkmcnt(7)
	v_mfma_f32_32x32x16_bf16 v[0:15], v[74:77], v[168:171], v[0:15]
	s_waitcnt lgkmcnt(6)
	v_mfma_f32_32x32x16_bf16 v[16:31], v[78:81], v[168:171], v[16:31]
	ds_read_b128 v[74:77], v42 offset:672
	ds_read_b128 v[78:81], v42 offset:33952
	s_waitcnt vmcnt(13) lgkmcnt(7)
	v_mfma_f32_32x32x16_bf16 v[0:15], v[82:85], v[172:175], v[0:15]
	s_waitcnt lgkmcnt(6)
	v_mfma_f32_32x32x16_bf16 v[16:31], v[86:89], v[172:175], v[16:31]
	ds_read_b128 v[82:85], v42 offset:704
	ds_read_b128 v[86:89], v42 offset:33984
	s_waitcnt vmcnt(12) lgkmcnt(7)
	v_mfma_f32_32x32x16_bf16 v[0:15], v[90:93], v[176:179], v[0:15]
	s_waitcnt lgkmcnt(6)
	v_mfma_f32_32x32x16_bf16 v[16:31], v[94:97], v[176:179], v[16:31]
	ds_read_b128 v[90:93], v42 offset:736
	ds_read_b128 v[94:97], v42 offset:34016
	s_waitcnt vmcnt(11) lgkmcnt(7)
	v_mfma_f32_32x32x16_bf16 v[0:15], v[66:69], v[180:183], v[0:15]
	s_waitcnt lgkmcnt(6)
	v_mfma_f32_32x32x16_bf16 v[16:31], v[70:73], v[180:183], v[16:31]
	ds_read_b128 v[66:69], v42 offset:768
	ds_read_b128 v[70:73], v42 offset:34048
	s_waitcnt vmcnt(10) lgkmcnt(7)
	v_mfma_f32_32x32x16_bf16 v[0:15], v[74:77], v[188:191], v[0:15]
	s_waitcnt lgkmcnt(6)
	v_mfma_f32_32x32x16_bf16 v[16:31], v[78:81], v[188:191], v[16:31]
	ds_read_b128 v[74:77], v42 offset:800
	ds_read_b128 v[78:81], v42 offset:34080
	s_waitcnt vmcnt(9) lgkmcnt(7)
	v_mfma_f32_32x32x16_bf16 v[0:15], v[82:85], v[192:195], v[0:15]
	s_waitcnt lgkmcnt(6)
	v_mfma_f32_32x32x16_bf16 v[16:31], v[86:89], v[192:195], v[16:31]
	ds_read_b128 v[82:85], v42 offset:832
	ds_read_b128 v[86:89], v42 offset:34112
	s_waitcnt vmcnt(8) lgkmcnt(7)
	v_mfma_f32_32x32x16_bf16 v[0:15], v[90:93], v[196:199], v[0:15]
	s_waitcnt lgkmcnt(6)
	v_mfma_f32_32x32x16_bf16 v[16:31], v[94:97], v[196:199], v[16:31]
	ds_read_b128 v[90:93], v42 offset:864
	ds_read_b128 v[94:97], v42 offset:34144
	s_waitcnt vmcnt(7) lgkmcnt(7)
	v_mfma_f32_32x32x16_bf16 v[0:15], v[66:69], v[200:203], v[0:15]
	s_waitcnt lgkmcnt(6)
	v_mfma_f32_32x32x16_bf16 v[16:31], v[70:73], v[200:203], v[16:31]
	ds_read_b128 v[66:69], v42 offset:896
	ds_read_b128 v[70:73], v42 offset:34176
	s_waitcnt vmcnt(6) lgkmcnt(7)
	v_mfma_f32_32x32x16_bf16 v[0:15], v[74:77], v[204:207], v[0:15]
	s_waitcnt lgkmcnt(6)
	v_mfma_f32_32x32x16_bf16 v[16:31], v[78:81], v[204:207], v[16:31]
	ds_read_b128 v[74:77], v42 offset:928
	ds_read_b128 v[78:81], v42 offset:34208
	s_waitcnt vmcnt(5) lgkmcnt(7)
	v_mfma_f32_32x32x16_bf16 v[0:15], v[82:85], v[208:211], v[0:15]
	s_waitcnt lgkmcnt(6)
	v_mfma_f32_32x32x16_bf16 v[16:31], v[86:89], v[208:211], v[16:31]
	ds_read_b128 v[82:85], v42 offset:960
	ds_read_b128 v[86:89], v42 offset:34240
	s_waitcnt vmcnt(4) lgkmcnt(7)
	v_mfma_f32_32x32x16_bf16 v[0:15], v[90:93], v[212:215], v[0:15]
	s_waitcnt lgkmcnt(6)
	v_mfma_f32_32x32x16_bf16 v[16:31], v[94:97], v[212:215], v[16:31]
	ds_read_b128 v[90:93], v42 offset:992
	ds_read_b128 v[94:97], v42 offset:34272
	s_waitcnt vmcnt(3) lgkmcnt(7)
	v_mfma_f32_32x32x16_bf16 v[0:15], v[66:69], v[216:219], v[0:15]
	s_waitcnt lgkmcnt(6)
	v_mfma_f32_32x32x16_bf16 v[16:31], v[70:73], v[216:219], v[16:31]
	s_waitcnt vmcnt(2) lgkmcnt(5)
	v_mfma_f32_32x32x16_bf16 v[0:15], v[74:77], v[220:223], v[0:15]
	s_waitcnt lgkmcnt(4)
	v_mfma_f32_32x32x16_bf16 v[16:31], v[78:81], v[220:223], v[16:31]
	v_lshlrev_b64 v[40:41], 9, v[32:33]
	v_lshl_add_u64 v[40:41], s[4:5], 0, v[40:41]
	v_lshl_add_u64 v[40:41], v[40:41], 0, s[0:1]
	v_lshl_add_u64 v[40:41], v[40:41], 0, v[38:39]
	s_waitcnt vmcnt(1) lgkmcnt(3)
	v_mfma_f32_32x32x16_bf16 v[0:15], v[82:85], v[224:227], v[0:15]
	s_waitcnt lgkmcnt(2)
	v_mfma_f32_32x32x16_bf16 v[16:31], v[86:89], v[224:227], v[16:31]
	s_waitcnt vmcnt(0) lgkmcnt(1)
	v_mfma_f32_32x32x16_bf16 v[0:15], v[90:93], v[228:231], v[0:15]
	s_waitcnt lgkmcnt(0)
	v_mfma_f32_32x32x16_bf16 v[16:31], v[94:97], v[228:231], v[16:31]
	s_nop 9
	global_store_dwordx4 v[40:41], v[0:3], off
	global_store_dwordx4 v[40:41], v[4:7], off offset:32
	global_store_dwordx4 v[40:41], v[8:11], off offset:64
	global_store_dwordx4 v[40:41], v[12:15], off offset:96
	global_store_dwordx4 v[40:41], v[16:19], off offset:128
	global_store_dwordx4 v[40:41], v[20:23], off offset:160
	global_store_dwordx4 v[40:41], v[24:27], off offset:192
	global_store_dwordx4 v[40:41], v[28:31], off offset:224
	s_cbranch_scc1 .LBB0_598
